# v23: v22 + sample memory-attention items split over two waves + sliding-window sample item V loads issued at the top of the tile
# baseline (speedup 1.0000x reference)
; DI float fexp2(float x) { return __builtin_amdgcn_exp2f(x); }
; DI u32x4 pack8(f32x4 a, f32x4 b) { u32x4 w; w.x = pk2(a[0], a[1]); w.y = pk2(a[2], a[3]); w.z = pk2(b[0], b[1]); w.w = pk2(b[2], b[3]); return w; }
; DI bf16x8 ld8f_bf(const float* p) { const f32x4 a = *(const f32x4*)p, b = *(const f32x4*)(p + 4); return __builtin_bit_cast(bf16x8, pack8(a, b)); }
; DI bf16x8 pack_step(const f32x16& x, int s) { u32x4 p; p.x = pk2(x[8 * s], x[8 * s + 1]); p.y = pk2(x[8 * s + 2], x[8 * s + 3]); p.z = pk2(x[8 * s + 4], x[8 * s + 5]); p.w = pk2(x[8 * s + 6], x[8 * s + 7]); return __builtin_bit_cast(bf16x8, p); }
; #define MFMA32(a, b, c) __builtin_amdgcn_mfma_f32_32x32x16_bf16((a), (b), (c), 0, 0, 0)
;     DI bf16x8 kfrag_t(int tl, int kk) const { const int lane = threadIdx.x & 63; return ld8f_bf(mk + ((size_t)(b * 256 + 32 * tl + (lane & 31)) * 4 + hd) * 128 + 16 * kk + 8 * (lane >> 5)); }
; template <class T> DI void attn_item(const T& t) {
;     ...
;         for (int i = 0; i < 16; ++i) { const float p = fexp2(s[i] - m); s[i] = p; ps += p; }
;         ps += __shfl_xor(ps, 32);
;         l += ps;
; #pragma unroll
;         for (int s2 = 0; s2 < 2; ++s2) { const bf16x8 pb = pack_step(s, s2);
;             if (T::VSPLIT) {
; #pragma unroll
;                 for (int dd = 0; dd < D / 32; ++dd) vf[s2][dd] = t.vfrag_t(tl, s2, dd);
;             }
; #pragma unroll
;             for (int dd = 0; dd < D / 32; ++dd) o[dd] = MFMA32(vf[s2][dd], pb, o[dd]); }
;     DI bf16x8 kfrag_t(int tl, int kk) const { const int lane = threadIdx.x & 63; return ld8f_bf(krow(ck, nk, 32 * tl + (lane & 31)) + 16 * kk + 8 * (lane >> 5)); }
; #pragma unroll
;         for (int j = 0; j < 4; ++j) { a[j] = krow(cv, nv, ka + j)[d]; c[j] = krow(cv, nv, ka + 8 + j)[d]; }
;         return __builtin_bit_cast(bf16x8, pack8(a, c)); }
.LBB0_853:
	v_sub_f32_e32 v49, v49, v72
	v_exp_f32_e32 v49, v49
	v_sub_f32_e32 v45, v45, v72
	v_exp_f32_e32 v45, v45
	v_sub_f32_e32 v46, v46, v72
	v_exp_f32_e32 v46, v46
	v_sub_f32_e32 v47, v47, v72
	v_exp_f32_e32 v47, v47
	v_sub_f32_e32 v48, v48, v72
	v_add_f32_e32 v82, 0, v49
	v_exp_f32_e32 v48, v48
	v_sub_f32_e32 v41, v41, v72
	v_add_f32_e32 v82, v45, v82
	v_exp_f32_e32 v83, v41
	v_sub_f32_e32 v41, v42, v72
	v_add_f32_e32 v82, v46, v82
	v_exp_f32_e32 v42, v41
	v_sub_f32_e32 v41, v43, v72
	v_add_f32_e32 v82, v47, v82
	v_exp_f32_e32 v43, v41
	v_sub_f32_e32 v41, v44, v72
	v_add_f32_e32 v82, v48, v82
	v_exp_f32_e32 v84, v41
	v_sub_f32_e32 v37, v37, v72
	v_add_f32_e32 v41, v83, v82
	v_exp_f32_e32 v82, v37
	v_sub_f32_e32 v37, v38, v72
	v_add_f32_e32 v41, v42, v41
	v_exp_f32_e32 v85, v37
	v_sub_f32_e32 v37, v39, v72
	v_add_f32_e32 v41, v43, v41
	v_exp_f32_e32 v86, v37
	v_sub_f32_e32 v37, v40, v72
	v_add_f32_e32 v41, v84, v41
	v_exp_f32_e32 v87, v37
	v_add_f32_e32 v37, v82, v41
	v_sub_f32_e32 v34, v34, v72
	v_add_f32_e32 v37, v85, v37
	v_exp_f32_e32 v89, v34
	v_sub_f32_e32 v34, v35, v72
	v_add_f32_e32 v37, v86, v37
	v_exp_f32_e32 v113, v34
	v_sub_f32_e32 v34, v36, v72
	v_add_f32_e32 v88, v87, v37
	v_exp_f32_e32 v125, v34
	v_cvt_pk_bf16_f32 v34, v49, v45
	s_waitcnt vmcnt(29)
	v_cvt_pk_bf16_f32 v38, v160, v162
	s_waitcnt vmcnt(21)
	v_cvt_pk_bf16_f32 v39, v168, v170
	v_cvt_pk_bf16_f32 v40, v161, v163
	s_waitcnt vmcnt(20)
	v_cvt_pk_bf16_f32 v41, v169, v171
	v_cvt_pk_bf16_f32 v37, v42, v43
	v_cvt_pk_bf16_f32 v42, v167, v165
	s_waitcnt vmcnt(16)
	v_cvt_pk_bf16_f32 v43, v175, v173
	v_cvt_pk_bf16_f32 v44, v166, v164
	v_cvt_pk_bf16_f32 v45, v174, v172
	v_cvt_pk_bf16_f32 v35, v46, v47
	v_cvt_pk_bf16_f32 v36, v48, v83
	s_add_i32 s27, s27, 1
	s_add_i32 s18, s18, 32
	v_mfma_f32_32x32x16_bf16 v[18:33], v[38:41], v[34:37], v[18:33]
	v_add_f32_e32 v38, v89, v88
	v_add_f32_e32 v38, v113, v38
	v_add_f32_e32 v46, v125, v38
	ds_bpermute_b32 v47, v70, v46
	s_cmpk_eq_i32 s18, 0xa0
	v_subrev_u32_e32 v69, 32, v69
	s_waitcnt vmcnt(13)
	v_cvt_pk_bf16_f32 v39, v141, v159
	v_mfma_f32_32x32x16_bf16 v[2:17], v[42:45], v[34:37], v[2:17]
	s_waitcnt vmcnt(12)
	v_cvt_pk_bf16_f32 v41, v158, v176
	v_cvt_pk_bf16_f32 v34, v84, v82
	s_waitcnt vmcnt(9)
	v_cvt_pk_bf16_f32 v38, v177, v179
	s_waitcnt vmcnt(8)
	v_cvt_pk_bf16_f32 v40, v178, v180
	v_cvt_pk_bf16_f32 v35, v85, v86
	v_cvt_pk_bf16_f32 v36, v87, v89
	s_waitcnt vmcnt(5)
	v_cvt_pk_bf16_f32 v44, v144, v148
	s_waitcnt vmcnt(4)
	v_cvt_pk_bf16_f32 v42, v142, v146
	v_cvt_pk_bf16_f32 v37, v113, v125
	s_waitcnt vmcnt(1)
	v_cvt_pk_bf16_f32 v45, v147, v143
	s_waitcnt vmcnt(0)
	v_cvt_pk_bf16_f32 v43, v149, v145
	v_mfma_f32_32x32x16_bf16 v[18:33], v[38:41], v[34:37], v[18:33]
	s_waitcnt lgkmcnt(0)
	v_add_f32_e32 v38, v46, v47
	v_add_f32_e32 v68, v68, v38
	v_mfma_f32_32x32x16_bf16 v[2:17], v[42:45], v[34:37], v[2:17]
	s_cbranch_scc1 .LBB0_856
.LBB0_854:
	s_cmp_lt_u32 s27, 4
	s_cselect_b64 s[84:85], -1, 0
	s_and_b64 s[84:85], s[84:85], exec
	s_cselect_b32 s86, s19, s26
	v_add_u32_e32 v141, s18, v1
	v_add_u32_e32 v142, s86, v141
	v_ashrrev_i32_e32 v143, 31, v142
	v_lshlrev_b64 v[144:145], 9, v[142:143]
	v_add_u32_e32 v143, 8, v141
	v_min_i32_e32 v143, 0x87, v143
	v_add_u32_e32 v146, s86, v143
	v_add_u32_e32 v143, 9, v141
	v_min_i32_e32 v143, 0x87, v143
	v_add_u32_e32 v150, s86, v143
	v_add_u32_e32 v143, 10, v141
	v_add_u32_e32 v156, 11, v141
	v_add_u32_e32 v148, 1, v142
	v_add_u32_e32 v152, 2, v142
	v_min_i32_e32 v143, 0x87, v143
	v_add_u32_e32 v142, 3, v142
	v_min_i32_e32 v156, 0x87, v156
	v_ashrrev_i32_e32 v147, 31, v146
	v_ashrrev_i32_e32 v149, 31, v148
	v_ashrrev_i32_e32 v151, 31, v150
	v_add_u32_e32 v154, s86, v143
	v_ashrrev_i32_e32 v143, 31, v142
	v_add_u32_e32 v156, s86, v156
	s_cselect_b32 s85, s15, s31
	s_cselect_b32 s84, s14, s30
	v_lshlrev_b64 v[146:147], 9, v[146:147]
	v_lshlrev_b64 v[148:149], 9, v[148:149]
	v_lshlrev_b64 v[150:151], 9, v[150:151]
	v_ashrrev_i32_e32 v153, 31, v152
	v_ashrrev_i32_e32 v155, 31, v154
	v_lshlrev_b64 v[142:143], 9, v[142:143]
	v_ashrrev_i32_e32 v157, 31, v156
	v_lshl_add_u64 v[144:145], s[84:85], 0, v[144:145]
	v_lshl_add_u64 v[146:147], s[84:85], 0, v[146:147]
	v_lshl_add_u64 v[148:149], s[84:85], 0, v[148:149]
	v_lshl_add_u64 v[150:151], s[84:85], 0, v[150:151]
	v_lshlrev_b64 v[152:153], 9, v[152:153]
	v_lshlrev_b64 v[154:155], 9, v[154:155]
	v_lshl_add_u64 v[142:143], s[84:85], 0, v[142:143]
	v_lshlrev_b64 v[156:157], 9, v[156:157]
	v_lshl_add_u64 v[144:145], v[144:145], 0, s[8:9]
	v_lshl_add_u64 v[146:147], v[146:147], 0, s[8:9]
	v_lshl_add_u64 v[148:149], v[148:149], 0, s[8:9]
	v_lshl_add_u64 v[150:151], v[150:151], 0, s[8:9]
	v_lshl_add_u64 v[152:153], s[84:85], 0, v[152:153]
	v_lshl_add_u64 v[154:155], s[84:85], 0, v[154:155]
	v_lshl_add_u64 v[142:143], v[142:143], 0, s[8:9]
	v_lshl_add_u64 v[156:157], s[84:85], 0, v[156:157]
	v_lshlrev_b32_e32 v158, 2, v116
	v_mov_b32_e32 v159, v115
	v_lshl_add_u64 v[152:153], v[152:153], 0, s[8:9]
	v_lshl_add_u64 v[154:155], v[154:155], 0, s[8:9]
	v_lshl_add_u64 v[156:157], v[156:157], 0, s[8:9]
	v_lshl_add_u64 v[144:145], v[144:145], 0, v[158:159]
	v_lshl_add_u64 v[146:147], v[146:147], 0, v[158:159]
	v_lshl_add_u64 v[148:149], v[148:149], 0, v[158:159]
	v_lshl_add_u64 v[150:151], v[150:151], 0, v[158:159]
	v_lshl_add_u64 v[142:143], v[142:143], 0, v[158:159]
	v_lshl_add_u64 v[152:153], v[152:153], 0, v[158:159]
	v_lshl_add_u64 v[154:155], v[154:155], 0, v[158:159]
	v_lshl_add_u64 v[156:157], v[156:157], 0, v[158:159]
	global_load_dword v160, v[144:145], off
	global_load_dword v161, v[146:147], off
	global_load_dword v162, v[148:149], off
; DI float fexp2(float x) { return __builtin_amdgcn_exp2f(x); }
; DI u32x4 pack8(f32x4 a, f32x4 b) { u32x4 w; w.x = pk2(a[0], a[1]); w.y = pk2(a[2], a[3]); w.z = pk2(b[0], b[1]); w.w = pk2(b[2], b[3]); return w; }
; DI bf16x8 ld8f_bf(const float* p) { const f32x4 a = *(const f32x4*)p, b = *(const f32x4*)(p + 4); return __builtin_bit_cast(bf16x8, pack8(a, b)); }
; DI int crow(int reg, int h) { return (reg & 3) + 8 * (reg >> 2) + 4 * h; }
;     DI void init_s(f32x16& s, int) const { zero16(s); }
;     DI bf16x8 kfrag_t(int tl, int kk) const { const int lane = threadIdx.x & 63; return ld8f_bf(mk + ((size_t)(b * 256 + 32 * tl + (lane & 31)) * 4 + hd) * 128 + 16 * kk + 8 * (lane >> 5)); }
;     DI void init_s(f32x16& s, int) const { zero16(s); }
;     DI bf16x8 kfrag_t(int tl, int kk) const { const int lane = threadIdx.x & 63; return ld8f_bf(krow(ck, nk, 32 * tl + (lane & 31)) + 16 * kk + 8 * (lane >> 5)); }
; #pragma unroll
;         for (int j = 0; j < 4; ++j) { a[j] = krow(cv, nv, ka + j)[d]; c[j] = krow(cv, nv, ka + 8 + j)[d]; }
;         return __builtin_bit_cast(bf16x8, pack8(a, c)); }
;     DI void init_s(f32x16& s, int) const { zero16(s); }
;     DI void post_s(f32x16& s, int tl, int r, int h) const { const float sl = fexp2(-(float)(kvh * 4 + (r >> 3) + 1)) * LOG2E;
; #pragma unroll
;         for (int i = 0; i < 16; ++i) { const int dist = 128 + (r & 7) - (32 * tl + crow(i, h)); s[i] = (dist >= 0 && dist < 128) ? s[i] - sl * (float)dist : -INFINITY; } }
	global_load_dword v163, v[150:151], off
	global_load_dword v164, v[150:151], off offset:128
	global_load_dword v165, v[148:149], off offset:128
	global_load_dword v166, v[146:147], off offset:128
	global_load_dword v167, v[144:145], off offset:128
	global_load_dword v168, v[152:153], off
	global_load_dword v169, v[154:155], off
	global_load_dword v170, v[142:143], off
	global_load_dword v171, v[156:157], off
	global_load_dword v172, v[156:157], off offset:128
	global_load_dword v173, v[142:143], off offset:128
	global_load_dword v174, v[154:155], off offset:128
	global_load_dword v175, v[152:153], off offset:128
	v_add_u32_e32 v142, 16, v141
	v_add_u32_e32 v144, 24, v141
	v_add_u32_e32 v146, 17, v141
	v_add_u32_e32 v148, 25, v141
	v_add_u32_e32 v150, 18, v141
	v_min_i32_e32 v142, 0x87, v142
	v_min_i32_e32 v144, 0x87, v144
	v_min_i32_e32 v146, 0x87, v146
	v_min_i32_e32 v148, 0x87, v148
	v_min_i32_e32 v150, 0x87, v150
	v_add_u32_e32 v152, 26, v141
	v_add_u32_e32 v154, 19, v141
	v_add_u32_e32 v141, 27, v141
	v_add_u32_e32 v142, s86, v142
	v_add_u32_e32 v144, s86, v144
	v_add_u32_e32 v146, s86, v146
	v_add_u32_e32 v148, s86, v148
	v_add_u32_e32 v150, s86, v150
	v_min_i32_e32 v152, 0x87, v152
	v_min_i32_e32 v154, 0x87, v154
	v_min_i32_e32 v141, 0x87, v141
	v_ashrrev_i32_e32 v143, 31, v142
	v_ashrrev_i32_e32 v145, 31, v144
	v_ashrrev_i32_e32 v147, 31, v146
	v_ashrrev_i32_e32 v149, 31, v148
	v_ashrrev_i32_e32 v151, 31, v150
	v_add_u32_e32 v152, s86, v152
	v_add_u32_e32 v154, s86, v154
	v_add_u32_e32 v156, s86, v141
	v_lshlrev_b64 v[142:143], 9, v[142:143]
	v_lshlrev_b64 v[144:145], 9, v[144:145]
	v_lshlrev_b64 v[146:147], 9, v[146:147]
	v_lshlrev_b64 v[148:149], 9, v[148:149]
	v_lshlrev_b64 v[150:151], 9, v[150:151]
	v_ashrrev_i32_e32 v153, 31, v152
	v_ashrrev_i32_e32 v155, 31, v154
	v_ashrrev_i32_e32 v157, 31, v156
	v_lshl_add_u64 v[142:143], s[84:85], 0, v[142:143]
	v_lshl_add_u64 v[144:145], s[84:85], 0, v[144:145]
	v_lshl_add_u64 v[146:147], s[84:85], 0, v[146:147]
	v_lshl_add_u64 v[148:149], s[84:85], 0, v[148:149]
	v_lshl_add_u64 v[150:151], s[84:85], 0, v[150:151]
	v_lshlrev_b64 v[152:153], 9, v[152:153]
	v_lshlrev_b64 v[154:155], 9, v[154:155]
	v_lshlrev_b64 v[156:157], 9, v[156:157]
	v_lshl_add_u64 v[142:143], v[142:143], 0, s[8:9]
	v_lshl_add_u64 v[144:145], v[144:145], 0, s[8:9]
	v_lshl_add_u64 v[146:147], v[146:147], 0, s[8:9]
	v_lshl_add_u64 v[148:149], v[148:149], 0, s[8:9]
	v_lshl_add_u64 v[150:151], v[150:151], 0, s[8:9]
	v_lshl_add_u64 v[152:153], s[84:85], 0, v[152:153]
	v_lshl_add_u64 v[154:155], s[84:85], 0, v[154:155]
	v_lshl_add_u64 v[156:157], s[84:85], 0, v[156:157]
	v_lshl_add_u64 v[152:153], v[152:153], 0, s[8:9]
	v_lshl_add_u64 v[154:155], v[154:155], 0, s[8:9]
	v_lshl_add_u64 v[156:157], v[156:157], 0, s[8:9]
	v_lshl_add_u64 v[142:143], v[142:143], 0, v[158:159]
	v_lshl_add_u64 v[144:145], v[144:145], 0, v[158:159]
	v_lshl_add_u64 v[146:147], v[146:147], 0, v[158:159]
	v_lshl_add_u64 v[148:149], v[148:149], 0, v[158:159]
	v_lshl_add_u64 v[150:151], v[150:151], 0, v[158:159]
	v_lshl_add_u64 v[152:153], v[152:153], 0, v[158:159]
	v_lshl_add_u64 v[154:155], v[154:155], 0, v[158:159]
	v_lshl_add_u64 v[156:157], v[156:157], 0, v[158:159]
	global_load_dword v141, v[150:151], off
	global_load_dword v158, v[152:153], off
	global_load_dword v159, v[154:155], off
	global_load_dword v176, v[156:157], off
	global_load_dword v177, v[142:143], off
	global_load_dword v178, v[144:145], off
	global_load_dword v179, v[146:147], off
	global_load_dword v180, v[148:149], off
	s_nop 0
	global_load_dword v148, v[148:149], off offset:128
	s_nop 0
	global_load_dword v146, v[146:147], off offset:128
	s_nop 0
	global_load_dword v144, v[144:145], off offset:128
	s_nop 0
	global_load_dword v142, v[142:143], off offset:128
	s_nop 0
	global_load_dword v143, v[156:157], off offset:128
	global_load_dword v145, v[154:155], off offset:128
	global_load_dword v147, v[152:153], off offset:128
	global_load_dword v149, v[150:151], off offset:128
	v_add_u32_e32 v34, s18, v116
	s_cmpk_eq_i32 s18, 0x80
	v_min_i32_e32 v34, 0x87, v34
	s_cselect_b32 s16, s26, s19
	v_add_u32_e32 v34, s16, v34
	v_ashrrev_i32_e32 v35, 31, v34
	s_cselect_b32 s17, s29, s13
	s_cselect_b32 s16, s28, s12
	v_lshlrev_b64 v[34:35], 9, v[34:35]
	v_lshl_add_u64 v[34:35], s[16:17], 0, v[34:35]
	v_lshl_add_u64 v[34:35], v[34:35], 0, s[8:9]
	v_lshl_add_u64 v[42:43], v[34:35], 0, v[114:115]
	global_load_dwordx4 v[34:37], v[42:43], off
	global_load_dwordx4 v[38:41], v[42:43], off offset:16
	global_load_dwordx4 v[74:77], v[42:43], off offset:64
	global_load_dwordx4 v[78:81], v[42:43], off offset:80
	global_load_dwordx4 v[82:85], v[42:43], off offset:128
	global_load_dwordx4 v[86:89], v[42:43], off offset:144
	global_load_dwordx4 v[90:93], v[42:43], off offset:192
	global_load_dwordx4 v[94:97], v[42:43], off offset:208
	v_add_u32_e32 v73, 27, v69
	v_add_u32_e32 v98, 26, v69
	v_add_u32_e32 v105, 11, v69
	v_cvt_f32_u32_e32 v113, v73
	v_add_u32_e32 v99, 25, v69
	v_add_u32_e32 v108, 8, v69
	v_cvt_f32_u32_e32 v112, v69
	v_cvt_f32_u32_e32 v125, v98
	v_add_u32_e32 v100, 24, v69
	v_add_u32_e32 v109, 3, v69
	v_cvt_f32_u32_e32 v126, v99
	v_add_u32_e32 v101, 19, v69
	v_add_u32_e32 v110, 2, v69
	v_cvt_f32_u32_e32 v127, v100
	v_add_u32_e32 v102, 18, v69
	v_add_u32_e32 v111, 1, v69
	v_cvt_f32_u32_e32 v128, v101
	v_cmp_gt_u32_e32 vcc, s34, v73
	v_add_u32_e32 v103, 17, v69
	v_add_u32_e32 v104, 16, v69
	v_cvt_f32_u32_e32 v129, v102
	v_cvt_f32_u32_e32 v138, v103
	v_cvt_f32_u32_e32 v139, v104
	v_add_u32_e32 v106, 10, v69
	v_add_u32_e32 v107, 9, v69
	s_waitcnt vmcnt(7)
; DI float fexp2(float x) { return __builtin_amdgcn_exp2f(x); }
; DI int crow(int reg, int h) { return (reg & 3) + 8 * (reg >> 2) + 4 * h; }
; #define MFMA32(a, b, c) __builtin_amdgcn_mfma_f32_32x32x16_bf16((a), (b), (c), 0, 0, 0)
;     DI bf16x8 kfrag_t(int tl, int kk) const { const int lane = threadIdx.x & 63; return ld8f_bf(krow(ck, nk, 32 * tl + (lane & 31)) + 16 * kk + 8 * (lane >> 5)); }
;     DI bf16x8 kfrag_t(int tl, int kk) const { const int lane = threadIdx.x & 63; return ld8f_bf(mk + ((size_t)(b * 256 + 32 * tl + (lane & 31)) * 4 + hd) * 128 + 16 * kk + 8 * (lane >> 5)); }
; template <class T> DI void attn_item(const T& t) {
;     ...
; #pragma unroll
;         for (int kk = 0; kk < D / 16; ++kk) s = MFMA32(kf[kk], qf[kk], s);
;         if (!T::VSPLIT && c + 1 < NCH) {
; #pragma unroll
;             for (int kk = 0; kk < D / 16; ++kk) kf[kk] = t.kfrag_t(tl + 1, kk); }
;         t.post_s(s, tl, r, h);
;         float mx = s[0];
; #pragma unroll
;         for (int i = 1; i < 16; ++i) mx = fmaxf(mx, s[i]);
;         mx = fmaxf(mx, __shfl_xor(mx, 32));
;         const bool need = mx > m + 8.0f;
;         if (__builtin_amdgcn_ballot_w64(need) != 0ull) {
;             const float mn = need ? mx : m;
;             const float sc = fexp2(m - mn);
;             l *= sc; m = mn;
; #pragma unroll
;             for (int dd = 0; dd < D / 32; ++dd)
; #pragma unroll
;                 for (int i = 0; i < 16; ++i) o[dd][i] *= sc;
;         }
;     DI void post_s(f32x16& s, int tl, int r, int h) const { const float sl = fexp2(-(float)(kvh * 4 + (r >> 3) + 1)) * LOG2E;
; #pragma unroll
;         for (int i = 0; i < 16; ++i) { const int dist = 128 + (r & 7) - (32 * tl + crow(i, h)); s[i] = (dist >= 0 && dist < 128) ? s[i] - sl * (float)dist : -INFINITY; } }
	v_cvt_pk_bf16_f32 v34, v34, v35
	v_cvt_pk_bf16_f32 v35, v36, v37
	s_waitcnt vmcnt(6)
	v_cvt_pk_bf16_f32 v36, v38, v39
	v_cvt_pk_bf16_f32 v37, v40, v41
	s_waitcnt vmcnt(5)
	v_cvt_pk_bf16_f32 v74, v74, v75
	v_cvt_pk_bf16_f32 v75, v76, v77
	v_mfma_f32_32x32x16_bf16 v[34:49], v[34:37], v[50:53], 0
	s_waitcnt vmcnt(4)
	v_cvt_pk_bf16_f32 v76, v78, v79
	v_cvt_pk_bf16_f32 v77, v80, v81
	s_waitcnt vmcnt(3)
	v_cvt_pk_bf16_f32 v78, v82, v83
	v_cvt_pk_bf16_f32 v79, v84, v85
	s_waitcnt vmcnt(2)
	v_cvt_pk_bf16_f32 v80, v86, v87
	v_cvt_pk_bf16_f32 v81, v88, v89
	v_cvt_f32_u32_e32 v82, v105
	v_mfma_f32_32x32x16_bf16 v[34:49], v[74:77], v[54:57], v[34:49]
	s_waitcnt vmcnt(1)
	v_cvt_pk_bf16_f32 v74, v90, v91
	v_cvt_pk_bf16_f32 v75, v92, v93
	s_waitcnt vmcnt(0)
	v_cvt_pk_bf16_f32 v76, v94, v95
	v_cvt_pk_bf16_f32 v77, v96, v97
	v_cvt_f32_u32_e32 v83, v106
	v_cvt_f32_u32_e32 v84, v107
	v_mfma_f32_32x32x16_bf16 v[34:49], v[78:81], v[58:61], v[34:49]
	v_cvt_f32_u32_e32 v78, v108
	v_cvt_f32_u32_e32 v79, v109
	v_cvt_f32_u32_e32 v80, v110
	v_cvt_f32_u32_e32 v81, v111
	v_mfma_f32_32x32x16_bf16 v[34:49], v[74:77], v[62:65], v[34:49]
	s_nop 11
	v_fma_f32 v34, -v71, v113, v34
	v_fma_f32 v35, -v71, v125, v35
	v_fma_f32 v75, -v71, v82, v42
	v_fma_f32 v82, -v71, v112, v49
	v_cndmask_b32_e32 v49, v137, v34, vcc
	v_cmp_gt_u32_e32 vcc, s34, v98
	v_fma_f32 v36, -v71, v126, v36
	v_fma_f32 v78, -v71, v78, v45
	v_cndmask_b32_e32 v45, v137, v35, vcc
	v_cmp_gt_u32_e32 vcc, s34, v99
	v_fma_f32 v37, -v71, v127, v37
	v_fma_f32 v79, -v71, v79, v46
	v_cndmask_b32_e32 v46, v137, v36, vcc
	v_cmp_gt_u32_e32 vcc, s34, v100
	v_fma_f32 v38, -v71, v128, v38
	v_fma_f32 v80, -v71, v80, v47
	v_cndmask_b32_e32 v47, v137, v37, vcc
	v_cmp_gt_u32_e32 vcc, s34, v101
	v_fma_f32 v39, -v71, v129, v39
	v_fma_f32 v81, -v71, v81, v48
	v_cndmask_b32_e32 v48, v137, v38, vcc
	v_cmp_gt_u32_e32 vcc, s34, v102
	v_fma_f32 v40, -v71, v138, v40
	v_fma_f32 v74, -v71, v139, v41
	v_cndmask_b32_e32 v41, v137, v39, vcc
	v_cmp_gt_u32_e32 vcc, s34, v103
	v_fma_f32 v76, -v71, v83, v43
	v_fma_f32 v77, -v71, v84, v44
	v_cndmask_b32_e32 v42, v137, v40, vcc
	v_cmp_gt_u32_e32 vcc, s34, v104
	v_max_f32_e32 v73, v49, v45
	v_max3_f32 v73, v73, v46, v47
	v_cndmask_b32_e32 v43, v137, v74, vcc
	v_cmp_gt_u32_e32 vcc, s34, v105
	v_max3_f32 v73, v73, v48, v41
	v_max3_f32 v73, v73, v42, v43
	v_cndmask_b32_e32 v44, v137, v75, vcc
	v_cmp_gt_u32_e32 vcc, s34, v106
	s_nop 1
	v_cndmask_b32_e32 v37, v137, v76, vcc
	v_cmp_gt_u32_e32 vcc, s34, v107
	v_max3_f32 v73, v73, v44, v37
	s_nop 0
	v_cndmask_b32_e32 v38, v137, v77, vcc
	v_cmp_gt_u32_e32 vcc, s34, v108
	s_nop 1
	v_cndmask_b32_e32 v39, v137, v78, vcc
	v_cmp_gt_u32_e32 vcc, s34, v109
	v_max3_f32 v73, v73, v38, v39
	s_nop 0
	v_cndmask_b32_e32 v40, v137, v79, vcc
	v_cmp_gt_u32_e32 vcc, s34, v110
	s_nop 1
	v_cndmask_b32_e32 v34, v137, v80, vcc
	v_cmp_gt_u32_e32 vcc, s34, v111
	v_max3_f32 v73, v73, v40, v34
	s_nop 0
	v_cndmask_b32_e32 v35, v137, v81, vcc
	v_cmp_gt_u32_e32 vcc, s34, v69
	s_nop 1
	v_cndmask_b32_e32 v36, v137, v82, vcc
	v_max3_f32 v73, v73, v35, v36
	ds_bpermute_b32 v74, v70, v73
	s_waitcnt lgkmcnt(0)
	v_max_f32_e32 v74, v74, v74
	v_max_f32_e32 v73, v73, v74
	v_add_f32_e32 v74, 0x41000000, v72
	v_cmp_gt_f32_e32 vcc, v73, v74
	s_cbranch_vccz .LBB0_853
	s_nop 0
	v_cndmask_b32_e32 v73, v72, v73, vcc
	v_sub_f32_e32 v72, v72, v73
	v_exp_f32_e32 v72, v72
	s_nop 0
	v_pk_mul_f32 v[32:33], v[32:33], v[72:73] op_sel_hi:[1,0]
	v_pk_mul_f32 v[30:31], v[30:31], v[72:73] op_sel_hi:[1,0]
	v_pk_mul_f32 v[28:29], v[28:29], v[72:73] op_sel_hi:[1,0]
	v_pk_mul_f32 v[26:27], v[26:27], v[72:73] op_sel_hi:[1,0]
	v_pk_mul_f32 v[24:25], v[24:25], v[72:73] op_sel_hi:[1,0]
	v_pk_mul_f32 v[22:23], v[22:23], v[72:73] op_sel_hi:[1,0]
	v_pk_mul_f32 v[20:21], v[20:21], v[72:73] op_sel_hi:[1,0]
	v_pk_mul_f32 v[18:19], v[18:19], v[72:73] op_sel_hi:[1,0]
	v_pk_mul_f32 v[16:17], v[16:17], v[72:73] op_sel_hi:[1,0]
	v_pk_mul_f32 v[14:15], v[14:15], v[72:73] op_sel_hi:[1,0]
	v_pk_mul_f32 v[12:13], v[12:13], v[72:73] op_sel_hi:[1,0]
	v_pk_mul_f32 v[10:11], v[10:11], v[72:73] op_sel_hi:[1,0]
	v_pk_mul_f32 v[8:9], v[8:9], v[72:73] op_sel_hi:[1,0]
	v_pk_mul_f32 v[6:7], v[6:7], v[72:73] op_sel_hi:[1,0]
	v_pk_mul_f32 v[4:5], v[4:5], v[72:73] op_sel_hi:[1,0]
	v_pk_mul_f32 v[2:3], v[2:3], v[72:73] op_sel_hi:[1,0]
	v_mul_f32_e32 v68, v68, v72
	v_mov_b32_e32 v72, v73
	s_branch .LBB0_853
